# attention loop 1 second half: row-sum adds and row-max tree moved from the post-barrier section into the preceding MFMA gaps
# speedup vs baseline: 1.0005x; 1.0005x over previous
.LBB0_813:
	ds_read_b128 v[98:101], v201 offset:13312
	ds_read_b128 v[102:105], v201 offset:13344
	v_add_u32_e32 v206, 0x6800, v179
	v_exp_f32_e32 v50, v50
	v_exp_f32_e32 v51, v51
	s_waitcnt lgkmcnt(1)
	v_mfma_f32_32x32x16_bf16 v[82:97], v[98:101], v[114:117], v[34:49]
	v_exp_f32_e32 v52, v52
	v_exp_f32_e32 v53, v53
	v_exp_f32_e32 v54, v54
	v_exp_f32_e32 v55, v55
	v_exp_f32_e32 v56, v56
	v_exp_f32_e32 v57, v57
	v_add_u32_e32 v207, 0x7800, v179
	s_waitcnt lgkmcnt(0)
	v_mfma_f32_32x32x16_bf16 v[82:97], v[102:105], v[118:121], v[82:97]
	ds_read_b128 v[98:101], v201 offset:13376
	ds_read_b128 v[102:105], v201 offset:13408
	v_exp_f32_e32 v58, v58
	v_exp_f32_e32 v59, v59
	v_exp_f32_e32 v60, v60
	v_exp_f32_e32 v61, v61
	v_exp_f32_e32 v62, v62
	v_exp_f32_e32 v63, v63
	s_waitcnt lgkmcnt(1)
	v_mfma_f32_32x32x16_bf16 v[82:97], v[98:101], v[122:125], v[82:97]
	v_exp_f32_e32 v64, v64
	v_exp_f32_e32 v65, v65
	v_exp_f32_e32 v66, v66
	v_exp_f32_e32 v67, v67
	v_exp_f32_e32 v68, v68
	v_exp_f32_e32 v69, v69
	v_exp_f32_e32 v70, v70
	s_waitcnt lgkmcnt(0)
	v_mfma_f32_32x32x16_bf16 v[82:97], v[102:105], v[126:129], v[82:97]
	ds_read_b128 v[98:101], v201 offset:13440
	ds_read_b128 v[102:105], v201 offset:13472
	ds_read_b128 v[170:173], v201 offset:19968
	ds_read_b128 v[174:177], v201 offset:20000
	v_exp_f32_e32 v71, v71
	v_exp_f32_e32 v72, v72
	v_exp_f32_e32 v73, v73
	v_exp_f32_e32 v74, v74
	v_exp_f32_e32 v75, v75
	s_waitcnt lgkmcnt(3)
	v_mfma_f32_32x32x16_bf16 v[82:97], v[98:101], v[130:133], v[82:97]
	v_exp_f32_e32 v76, v76
	v_exp_f32_e32 v77, v77
	v_exp_f32_e32 v78, v78
	v_exp_f32_e32 v79, v79
	v_exp_f32_e32 v80, v80
	v_exp_f32_e32 v81, v81
	s_waitcnt lgkmcnt(2)
	v_mfma_f32_32x32x16_bf16 v[82:97], v[102:105], v[134:137], v[82:97]
	s_waitcnt lgkmcnt(1)
	v_mfma_f32_32x32x16_bf16 v[98:113], v[170:173], v[114:117], v[34:49]
	v_add_f32_e32 v250, v50, v66
	v_add_f32_e32 v251, v51, v67
	v_add_f32_e32 v250, v250, v52
	v_add_f32_e32 v251, v251, v53
	v_add_f32_e32 v250, v250, v54
	s_waitcnt lgkmcnt(0)
	v_mfma_f32_32x32x16_bf16 v[98:113], v[174:177], v[118:121], v[98:113]
	ds_read_b128 v[170:173], v201 offset:20032
	ds_read_b128 v[174:177], v201 offset:20064
	v_add_f32_e32 v251, v251, v55
	v_add_f32_e32 v250, v250, v56
	v_add_f32_e32 v251, v251, v57
	v_add_f32_e32 v250, v250, v58
	v_add_f32_e32 v251, v251, v59
	s_waitcnt lgkmcnt(1)
	v_mfma_f32_32x32x16_bf16 v[98:113], v[170:173], v[122:125], v[98:113]
	v_add_f32_e32 v250, v250, v60
	v_add_f32_e32 v251, v251, v61
	v_add_f32_e32 v250, v250, v62
	v_add_f32_e32 v251, v251, v63
	v_add_f32_e32 v250, v250, v64
	s_waitcnt lgkmcnt(0)
	v_mfma_f32_32x32x16_bf16 v[98:113], v[174:177], v[126:129], v[98:113]
	ds_read_b128 v[170:173], v201 offset:20096
	ds_read_b128 v[174:177], v201 offset:20128
	ds_read2_b64 v[180:183], v206 offset0:4 offset1:6
	v_add_f32_e32 v251, v251, v65
	v_add_f32_e32 v250, v250, v68
	v_add_f32_e32 v251, v251, v69
	v_add_f32_e32 v250, v250, v70
	v_add_f32_e32 v251, v251, v71
	s_waitcnt lgkmcnt(2)
	v_mfma_f32_32x32x16_bf16 v[98:113], v[170:173], v[130:133], v[98:113]
	ds_read2_b64 v[170:173], v206 offset1:2
	v_add_f32_e32 v250, v250, v72
	v_add_f32_e32 v251, v251, v73
	v_add_f32_e32 v250, v250, v74
	v_add_f32_e32 v251, v251, v75
	v_add_f32_e32 v250, v250, v76
	s_waitcnt lgkmcnt(2)
	v_mfma_f32_32x32x16_bf16 v[98:113], v[174:177], v[134:137], v[98:113]
	v_add_f32_e32 v251, v251, v77
	v_add_f32_e32 v250, v250, v78
	v_add_f32_e32 v251, v251, v79
	v_add_f32_e32 v250, v250, v80
	v_add_f32_e32 v251, v251, v81
	v_cvt_pk_bf16_f32 v174, v50, v51
	v_cvt_pk_bf16_f32 v175, v52, v53
	v_cvt_pk_bf16_f32 v176, v54, v55
	v_cvt_pk_bf16_f32 v177, v56, v57
	s_waitcnt lgkmcnt(0)
	s_nop 0
	v_mfma_f32_32x32x16_bf16 v[2:17], v[170:173], v[174:177], v[2:17]
	ds_read2_b64 v[170:173], v207 offset0:32 offset1:34
	v_max_f32_e32 v252, v82, v83
	v_max_f32_e32 v253, v84, v85
	s_waitcnt lgkmcnt(0)
	v_mfma_f32_32x32x16_bf16 v[18:33], v[170:173], v[174:177], v[18:33]
	ds_read2_b64 v[174:177], v207 offset0:36 offset1:38
	v_max3_f32 v252, v252, v86, v87
	v_max3_f32 v253, v253, v88, v89
	v_cvt_pk_bf16_f32 v170, v58, v59
	v_cvt_pk_bf16_f32 v171, v60, v61
	v_cvt_pk_bf16_f32 v172, v62, v63
	v_cvt_pk_bf16_f32 v173, v64, v65
	s_nop 1
	v_mfma_f32_32x32x16_bf16 v[2:17], v[180:183], v[170:173], v[2:17]
	ds_read2_b64 v[180:183], v206 offset0:8 offset1:10
	v_max3_f32 v252, v252, v90, v91
	v_max3_f32 v253, v253, v92, v93
	s_waitcnt lgkmcnt(1)
	v_mfma_f32_32x32x16_bf16 v[18:33], v[174:177], v[170:173], v[18:33]
	ds_read2_b64 v[174:177], v207 offset0:40 offset1:42
	v_max3_f32 v252, v252, v94, v95
	v_max3_f32 v253, v253, v96, v97
	v_cvt_pk_bf16_f32 v170, v66, v67
	v_cvt_pk_bf16_f32 v171, v68, v69
	v_cvt_pk_bf16_f32 v172, v70, v71
	v_cvt_pk_bf16_f32 v173, v72, v73
	s_waitcnt lgkmcnt(1)
	s_nop 0
	v_mfma_f32_32x32x16_bf16 v[2:17], v[180:183], v[170:173], v[2:17]
	ds_read2_b64 v[180:183], v206 offset0:12 offset1:14
	v_max3_f32 v252, v252, v98, v99
	v_max3_f32 v253, v253, v100, v101
	s_waitcnt lgkmcnt(1)
	v_mfma_f32_32x32x16_bf16 v[18:33], v[174:177], v[170:173], v[18:33]
	ds_read2_b64 v[174:177], v207 offset0:44 offset1:46
	v_max3_f32 v252, v252, v102, v103
	v_max3_f32 v253, v253, v104, v105
	v_cvt_pk_bf16_f32 v170, v74, v75
	v_cvt_pk_bf16_f32 v171, v76, v77
	v_cvt_pk_bf16_f32 v172, v78, v79
	v_cvt_pk_bf16_f32 v173, v80, v81
	s_waitcnt vmcnt(1)
	ds_write_b128 v190, v[142:145]
	s_waitcnt lgkmcnt(2)
	v_mfma_f32_32x32x16_bf16 v[2:17], v[180:183], v[170:173], v[2:17]
	v_max3_f32 v252, v252, v106, v107
	v_max3_f32 v253, v253, v108, v109
	s_waitcnt lgkmcnt(1)
	v_mfma_f32_32x32x16_bf16 v[18:33], v[174:177], v[170:173], v[18:33]
	v_max3_f32 v252, v252, v110, v111
	v_max3_f32 v253, v253, v112, v113
	s_and_saveexec_b64 s[8:9], s[6:7]
	v_add_u32_e32 v142, v159, v191
	ds_write_b128 v142, v[138:141]
	s_or_b64 exec, exec, s[8:9]
	v_add3_u32 v208, v0, v158, s4
	s_waitcnt vmcnt(0)
	ds_write2_b64 v208, v[146:147], v[148:149] offset1:1
	s_waitcnt lgkmcnt(0)
	s_barrier
	global_load_dwordx4 v[142:145], v152, s[54:55]
	s_and_saveexec_b64 s[8:9], s[6:7]
	s_cbranch_execz .LBB0_817
	global_load_dwordx4 v[138:141], v150, s[54:55]
.LBB0_817:
	s_or_b64 exec, exec, s[8:9]
	global_load_dwordx4 v[146:149], v160, s[56:57] offset:256
	v_max_f32_e32 v51, v252, v253
	v_add_f32_e32 v250, v250, v251
	v_add_u32_e32 v150, 0x6000, v150
	v_mov_b32_e32 v52, v51
	v_add_u32_e32 v152, 0x6000, v152
	v_add_u32_e32 v160, 0x100, v160
	v_permlane32_swap_b32_e32 v51, v52
	v_add_f32_e32 v180, v203, v250
	v_max_f32_e32 v51, v51, v52
	v_cmp_lt_f32_e32 vcc, s97, v51
	s_cbranch_vccnz .Lat1_resc_b
	v_mov_b32_e32 v205, v204
